# v043 + prompt scan loop trimmed by 19 instructions per 4 steps (row_ror:8 adds fused into DPP adds, zero-add copies and packed-add shuffles removed, y-store address pre-offset)
# speedup vs baseline: 1.0090x; 1.0090x over previous
.LBB0_360:
	s_waitcnt vmcnt(1)
	v_mov_b64_e32 v[42:43], v[22:23]
	s_waitcnt vmcnt(0)
	v_mov_b64_e32 v[46:47], v[18:19]
	s_sub_i32 s24, 0x810, s4
	s_and_b32 s47, s27, 1
	v_mov_b64_e32 v[40:41], v[20:21]
	v_mov_b64_e32 v[44:45], v[16:17]
	s_min_i32 s24, s24, 32
	v_lshl_add_u32 v132, s47, 12, v236
	s_setprio 3
	s_cmpk_gt_i32 s4, 0x80f
	v_mov_b32_e32 v131, 0
	s_cbranch_scc1 .LBB0_371
	s_mul_i32 s47, s47, 0xb000
	s_add_i32 s28, s47, 0
	v_lshl_add_u32 v134, v192, 2, s28
	v_add_u32_e32 v72, 0xa000, v134
	v_add_u32_e32 v133, s28, v196
	ds_read2_b64 v[16:19], v72 offset1:16
	ds_read_b128 v[20:23], v133 offset:33024
	ds_read_b128 v[24:27], v133 offset:32768
	ds_read_b128 v[28:31], v133 offset:24832
	ds_read_b128 v[48:51], v133 offset:24576
	ds_read_b128 v[52:55], v133 offset:16640
	ds_read_b128 v[56:59], v133 offset:16384
	ds_read_b128 v[60:63], v133 offset:8448
	ds_read_b128 v[64:67], v133 offset:8192
	ds_read_b128 v[68:71], v133 offset:256
	ds_read_b128 v[112:115], v133
	ds_read2_b64 v[80:83], v72 offset0:32 offset1:48
	ds_read_b128 v[104:107], v133 offset:512
	ds_read_b128 v[84:87], v133 offset:768
	ds_read_b128 v[120:123], v133 offset:8704
	ds_read_b128 v[92:95], v133 offset:8960
	ds_read_b128 v[96:99], v133 offset:16896
	ds_read_b128 v[72:75], v133 offset:17152
	ds_read_b128 v[108:111], v133 offset:25088
	ds_read_b128 v[88:91], v133 offset:25344
	ds_read_b128 v[100:103], v133 offset:33280
	ds_read_b128 v[76:79], v133 offset:33536
	s_waitcnt lgkmcnt(13)
	v_pk_mul_f32 v[116:117], v[202:203], v[66:67]
	v_pk_mul_f32 v[66:67], v[206:207], v[66:67]
	v_pk_fma_f32 v[116:117], v[204:205], v[64:65], v[116:117]
	v_pk_fma_f32 v[64:65], v[208:209], v[64:65], v[66:67]
	v_add_f32_e32 v66, v116, v117
	v_add_f32_e32 v64, v64, v65
	s_waitcnt lgkmcnt(11)
	v_pk_mul_f32 v[116:117], v[206:207], v[114:115]
	v_add_f32_dpp v65, v66, v66 quad_perm:[1,0,3,2] row_mask:0xf bank_mask:0xf bound_ctrl:1
	v_add_f32_dpp v64, v64, v64 quad_perm:[1,0,3,2] row_mask:0xf bank_mask:0xf bound_ctrl:1
	v_pk_fma_f32 v[116:117], v[16:17], v[50:51], v[116:117] op_sel:[1,0,0]
	v_add_f32_dpp v65, v65, v65 quad_perm:[2,3,0,1] row_mask:0xf bank_mask:0xf bound_ctrl:1
	v_add_f32_dpp v64, v64, v64 quad_perm:[2,3,0,1] row_mask:0xf bank_mask:0xf bound_ctrl:1
	s_nop 0
	v_add_f32_dpp v118, v65, v65 row_ror:4 row_mask:0xf bank_mask:0xf bound_ctrl:1
	v_add_f32_dpp v66, v64, v64 row_ror:4 row_mask:0xf bank_mask:0xf bound_ctrl:1
	v_pk_mul_f32 v[64:65], v[208:209], v[112:113]
	v_pk_mul_f32 v[112:113], v[204:205], v[112:113]
	v_pk_fma_f32 v[64:65], v[16:17], v[48:49], v[64:65] op_sel:[1,0,0]
	v_add_f32_dpp v66, v66, v66 row_ror:8 row_mask:0xf bank_mask:0xf bound_ctrl:1
	v_pk_fma_f32 v[48:49], v[16:17], v[48:49], v[112:113] op_sel_hi:[0,1,1]
	v_add_f32_dpp v112, v118, v118 row_ror:8 row_mask:0xf bank_mask:0xf bound_ctrl:1
	v_pk_fma_f32 v[64:65], v[56:57], v[66:67], v[64:65] op_sel_hi:[1,0,1] neg_lo:[1,0,0] neg_hi:[1,0,0]
	v_pk_fma_f32 v[48:49], v[56:57], v[112:113], v[48:49] op_sel_hi:[1,0,1] neg_lo:[1,0,0] neg_hi:[1,0,0]
	v_pk_mul_f32 v[56:57], v[202:203], v[114:115]
	v_pk_fma_f32 v[66:67], v[58:59], v[66:67], v[116:117] op_sel_hi:[1,0,1] neg_lo:[1,0,0] neg_hi:[1,0,0]
	v_pk_fma_f32 v[16:17], v[16:17], v[50:51], v[56:57] op_sel_hi:[0,1,1]
	v_pk_fma_f32 v[16:17], v[58:59], v[112:113], v[16:17] op_sel_hi:[1,0,1] neg_lo:[1,0,0] neg_hi:[1,0,0]
	v_pk_mul_f32 v[116:117], v[26:27], v[66:67]
	v_pk_mul_f32 v[26:27], v[26:27], v[16:17]
	v_pk_fma_f32 v[116:117], v[24:25], v[64:65], v[116:117]
	v_pk_fma_f32 v[24:25], v[24:25], v[48:49], v[26:27]
	v_pk_mul_f32 v[26:27], v[62:63], v[66:67]
	v_add_f32_e32 v131, v24, v25
	v_pk_mul_f32 v[24:25], v[62:63], v[16:17]
	v_pk_fma_f32 v[26:27], v[60:61], v[64:65], v[26:27]
	v_pk_fma_f32 v[24:25], v[60:61], v[48:49], v[24:25]
	v_add_f32_e32 v51, v26, v27
	v_add_f32_e32 v50, v24, v25
	v_pk_mul_f32 v[24:25], v[68:69], v[48:49]
	v_pk_mul_f32 v[26:27], v[68:69], v[64:65]
	v_pk_fma_f32 v[24:25], v[18:19], v[28:29], v[24:25] op_sel_hi:[0,1,1]
	v_pk_mul_f32 v[16:17], v[70:71], v[16:17]
	v_pk_fma_f32 v[26:27], v[18:19], v[28:29], v[26:27] op_sel:[1,0,0]
	v_pk_mul_f32 v[28:29], v[70:71], v[66:67]
	v_pk_fma_f32 v[16:17], v[18:19], v[30:31], v[16:17] op_sel_hi:[0,1,1]
	v_pk_fma_f32 v[18:19], v[18:19], v[30:31], v[28:29] op_sel:[1,0,0]
	v_add_f32_dpp v28, v50, v50 quad_perm:[1,0,3,2] row_mask:0xf bank_mask:0xf bound_ctrl:1
	v_add_f32_dpp v29, v51, v51 quad_perm:[1,0,3,2] row_mask:0xf bank_mask:0xf bound_ctrl:1
	v_add_f32_e32 v130, v116, v117
	v_add_f32_dpp v28, v28, v28 quad_perm:[2,3,0,1] row_mask:0xf bank_mask:0xf bound_ctrl:1
	v_add_f32_dpp v29, v29, v29 quad_perm:[2,3,0,1] row_mask:0xf bank_mask:0xf bound_ctrl:1
	s_nop 0
	v_add_f32_dpp v28, v28, v28 row_ror:4 row_mask:0xf bank_mask:0xf bound_ctrl:1
	v_add_f32_dpp v29, v29, v29 row_ror:4 row_mask:0xf bank_mask:0xf bound_ctrl:1
	s_nop 0
	v_add_f32_dpp v28, v28, v28 row_ror:8 row_mask:0xf bank_mask:0xf bound_ctrl:1
	v_add_f32_dpp v30, v29, v29 row_ror:8 row_mask:0xf bank_mask:0xf bound_ctrl:1
	v_pk_fma_f32 v[114:115], v[54:55], v[28:29], v[16:17] op_sel_hi:[1,0,1] neg_lo:[1,0,0] neg_hi:[1,0,0]
	v_pk_fma_f32 v[112:113], v[54:55], v[30:31], v[18:19] op_sel_hi:[1,0,1] neg_lo:[1,0,0] neg_hi:[1,0,0]
	v_pk_fma_f32 v[118:119], v[52:53], v[28:29], v[24:25] op_sel_hi:[1,0,1] neg_lo:[1,0,0] neg_hi:[1,0,0]
	v_pk_fma_f32 v[116:117], v[52:53], v[30:31], v[26:27] op_sel_hi:[1,0,1] neg_lo:[1,0,0] neg_hi:[1,0,0]
	v_pk_mul_f32 v[16:17], v[22:23], v[114:115]
	v_pk_mul_f32 v[18:19], v[22:23], v[112:113]
	v_pk_fma_f32 v[16:17], v[20:21], v[118:119], v[16:17]
	v_pk_fma_f32 v[18:19], v[20:21], v[116:117], v[18:19]
	v_add_f32_e32 v135, v16, v17
	v_add_f32_e32 v136, v18, v19
	s_cmpk_lt_i32 s4, 0x80c
	s_cselect_b64 s[78:79], -1, 0
	s_and_b64 s[28:29], s[78:79], exec
	s_cselect_b32 s28, 4, 0
	v_lshl_add_u32 v16, s28, 8, v133
	v_lshl_add_u32 v17, s28, 7, v134
	s_or_b32 s28, s28, 1
	v_lshl_add_u32 v56, s28, 8, v133
	ds_read_b128 v[68:71], v16 offset:8192
	ds_read_b128 v[28:31], v16 offset:16384
	ds_read_b128 v[60:63], v16
	ds_read_b128 v[52:55], v16 offset:32768
	ds_read_b128 v[64:67], v16 offset:24576
	ds_read_b64 v[126:127], v17 offset:40960
	ds_read_b128 v[48:51], v56 offset:8192
	ds_read_b128 v[16:19], v56 offset:16384
	ds_read_b128 v[24:27], v56
	ds_read_b128 v[20:23], v56 offset:32768
	v_lshl_add_u32 v124, s28, 7, v134
	ds_read_b128 v[56:59], v56 offset:24576
	ds_read_b64 v[124:125], v124 offset:40960
	s_waitcnt lgkmcnt(14)
	v_pk_mul_f32 v[128:129], v[122:123], v[114:115]
	v_pk_mul_f32 v[122:123], v[122:123], v[112:113]
	v_pk_fma_f32 v[128:129], v[120:121], v[118:119], v[128:129]
	v_pk_fma_f32 v[120:121], v[120:121], v[116:117], v[122:123]
	v_add_f32_e32 v122, v128, v129
	v_cndmask_b32_e64 v128, v131, v130, s[6:7]
	v_cndmask_b32_e64 v129, v135, v136, s[6:7]
	v_cndmask_b32_e64 v130, v130, v131, s[6:7]
	v_cndmask_b32_e64 v131, v136, v135, s[6:7]
	v_add_f32_e32 v120, v120, v121
	v_add_f32_dpp v128, v128, v130 quad_perm:[1,0,3,2] row_mask:0xf bank_mask:0xf bound_ctrl:1
	v_add_f32_dpp v129, v129, v131 quad_perm:[1,0,3,2] row_mask:0xf bank_mask:0xf bound_ctrl:1
	v_add_f32_dpp v121, v122, v122 quad_perm:[1,0,3,2] row_mask:0xf bank_mask:0xf bound_ctrl:1
	v_add_f32_dpp v120, v120, v120 quad_perm:[1,0,3,2] row_mask:0xf bank_mask:0xf bound_ctrl:1
	v_cndmask_b32_e64 v130, v128, v129, s[8:9]
	v_cndmask_b32_e64 v128, v129, v128, s[8:9]
	v_add_f32_dpp v121, v121, v121 quad_perm:[2,3,0,1] row_mask:0xf bank_mask:0xf bound_ctrl:1
	v_add_f32_dpp v122, v120, v120 quad_perm:[2,3,0,1] row_mask:0xf bank_mask:0xf bound_ctrl:1
	v_add_f32_dpp v128, v130, v128 quad_perm:[2,3,0,1] row_mask:0xf bank_mask:0xf bound_ctrl:1
	v_add_f32_dpp v120, v121, v121 row_ror:4 row_mask:0xf bank_mask:0xf bound_ctrl:1
	v_add_f32_dpp v121, v122, v122 row_ror:4 row_mask:0xf bank_mask:0xf bound_ctrl:1
	v_mov_b32_e32 v122, v177
	v_mov_b32_e32 v123, v177
	v_add_f32_dpp v128, v128, v128 row_ror:4 row_mask:0xf bank_mask:0xf bound_ctrl:1
	v_mov_b32_e32 v129, v177
	v_mov_b32_dpp v122, v120 row_ror:8 row_mask:0xf bank_mask:0xf
	v_mov_b32_dpp v123, v121 row_ror:8 row_mask:0xf bank_mask:0xf
	v_mov_b32_dpp v129, v128 row_ror:8 row_mask:0xf bank_mask:0xf
	s_and_saveexec_b64 s[80:81], s[10:11]
	v_add3_u32 v130, v132, v197, v240
	v_add_f32_e32 v128, v128, v129
	ds_write_b32 v130, v128
	s_or_b64 exec, exec, s[80:81]
	v_pk_mul_f32 v[118:119], v[104:105], v[118:119]
	v_pk_mul_f32 v[114:115], v[106:107], v[114:115]
	v_pk_mul_f32 v[104:105], v[104:105], v[116:117]
	v_pk_mul_f32 v[106:107], v[106:107], v[112:113]
	v_pk_fma_f32 v[118:119], v[108:109], v[80:81], v[118:119] op_sel_hi:[1,0,1]
	v_pk_fma_f32 v[114:115], v[110:111], v[80:81], v[114:115] op_sel_hi:[1,0,1]
	v_pk_fma_f32 v[104:105], v[108:109], v[80:81], v[104:105] op_sel:[0,1,0]
	v_pk_fma_f32 v[80:81], v[110:111], v[80:81], v[106:107] op_sel:[0,1,0]
	v_add_f32_e32 v106, v120, v122
	v_add_f32_e32 v108, v121, v123
	v_pk_fma_f32 v[110:111], v[96:97], v[106:107], v[118:119] op_sel_hi:[1,0,1] neg_lo:[1,0,0] neg_hi:[1,0,0]
	v_pk_fma_f32 v[106:107], v[98:99], v[106:107], v[114:115] op_sel_hi:[1,0,1] neg_lo:[1,0,0] neg_hi:[1,0,0]
	v_pk_fma_f32 v[80:81], v[98:99], v[108:109], v[80:81] op_sel_hi:[1,0,1] neg_lo:[1,0,0] neg_hi:[1,0,0]
	v_pk_fma_f32 v[96:97], v[96:97], v[108:109], v[104:105] op_sel_hi:[1,0,1] neg_lo:[1,0,0] neg_hi:[1,0,0]
	s_waitcnt lgkmcnt(13)
	v_pk_mul_f32 v[98:99], v[102:103], v[106:107]
	v_pk_mul_f32 v[102:103], v[102:103], v[80:81]
	v_pk_fma_f32 v[98:99], v[100:101], v[110:111], v[98:99]
	v_pk_fma_f32 v[100:101], v[100:101], v[96:97], v[102:103]
	v_mov_b32_e32 v103, v98
	v_mov_b32_e32 v102, v100
	v_mov_b32_e32 v98, v101
	v_pk_add_f32 v[128:129], v[102:103], v[98:99]
	v_pk_mul_f32 v[98:99], v[94:95], v[106:107]
	v_pk_mul_f32 v[94:95], v[94:95], v[80:81]
	v_pk_fma_f32 v[98:99], v[92:93], v[110:111], v[98:99]
	v_pk_fma_f32 v[92:93], v[92:93], v[96:97], v[94:95]
	v_add_f32_e32 v98, v98, v99
	v_add_f32_e32 v99, v92, v93
	v_pk_mul_f32 v[92:93], v[84:85], v[110:111]
	v_pk_mul_f32 v[94:95], v[86:87], v[106:107]
	v_pk_mul_f32 v[84:85], v[84:85], v[96:97]
	v_pk_mul_f32 v[80:81], v[86:87], v[80:81]
	v_pk_fma_f32 v[92:93], v[88:89], v[82:83], v[92:93] op_sel_hi:[1,0,1]
	v_pk_fma_f32 v[94:95], v[90:91], v[82:83], v[94:95] op_sel_hi:[1,0,1]
	v_pk_fma_f32 v[84:85], v[88:89], v[82:83], v[84:85] op_sel:[0,1,0]
	v_pk_fma_f32 v[80:81], v[90:91], v[82:83], v[80:81] op_sel:[0,1,0]
	v_add_f32_dpp v82, v98, v98 quad_perm:[1,0,3,2] row_mask:0xf bank_mask:0xf bound_ctrl:1
	v_add_f32_dpp v83, v99, v99 quad_perm:[1,0,3,2] row_mask:0xf bank_mask:0xf bound_ctrl:1
	s_nop 0
	v_add_f32_dpp v82, v82, v82 quad_perm:[2,3,0,1] row_mask:0xf bank_mask:0xf bound_ctrl:1
	v_add_f32_dpp v83, v83, v83 quad_perm:[2,3,0,1] row_mask:0xf bank_mask:0xf bound_ctrl:1
	s_nop 0
	v_add_f32_dpp v82, v82, v82 row_ror:4 row_mask:0xf bank_mask:0xf bound_ctrl:1
	v_add_f32_dpp v83, v83, v83 row_ror:4 row_mask:0xf bank_mask:0xf bound_ctrl:1
	s_nop 0
	v_add_f32_dpp v82, v82, v82 row_ror:8 row_mask:0xf bank_mask:0xf bound_ctrl:1
	v_add_f32_dpp v86, v83, v83 row_ror:8 row_mask:0xf bank_mask:0xf bound_ctrl:1
	v_pk_fma_f32 v[90:91], v[74:75], v[82:83], v[94:95] op_sel_hi:[1,0,1] neg_lo:[1,0,0] neg_hi:[1,0,0]
	v_pk_fma_f32 v[94:95], v[74:75], v[86:87], v[80:81] op_sel_hi:[1,0,1] neg_lo:[1,0,0] neg_hi:[1,0,0]
	v_pk_fma_f32 v[88:89], v[72:73], v[82:83], v[92:93] op_sel_hi:[1,0,1] neg_lo:[1,0,0] neg_hi:[1,0,0]
	v_pk_fma_f32 v[92:93], v[72:73], v[86:87], v[84:85] op_sel_hi:[1,0,1] neg_lo:[1,0,0] neg_hi:[1,0,0]
	s_waitcnt lgkmcnt(12)
	v_pk_mul_f32 v[72:73], v[78:79], v[90:91]
	v_pk_mul_f32 v[74:75], v[78:79], v[94:95]
	v_pk_fma_f32 v[72:73], v[76:77], v[88:89], v[72:73]
	v_pk_fma_f32 v[74:75], v[76:77], v[92:93], v[74:75]
	v_mov_b32_e32 v77, v72
	v_mov_b32_e32 v76, v74
	v_mov_b32_e32 v72, v75
	v_pk_add_f32 v[130:131], v[76:77], v[72:73]
	s_andn2_b64 vcc, exec, s[78:79]
	s_cbranch_vccnz .LBB0_372
	v_cndmask_b32_e64 v72, 0, 1, s[72:73]
	s_mov_b32 s28, 0xb000
	v_lshl_or_b32 v135, v72, 12, v241
	v_add_u32_e32 v135, 0x16100, v135
	v_mul_lo_u32 v72, v72, s28
	v_add_u32_e32 v136, v242, v72
	v_or_b32_e32 v137, v243, v72
	s_mov_b32 s47, 4
.LBB0_365:
	ds_read2_b64 v[80:83], v136 offset1:16
	ds_read_b128 v[112:115], v137
	ds_read_b128 v[84:87], v137 offset:256
	ds_read_b128 v[120:123], v137 offset:8192
	ds_read_b128 v[100:103], v137 offset:8448
	ds_read_b128 v[104:107], v137 offset:16384
	ds_read_b128 v[72:75], v137 offset:16640
	ds_read_b128 v[116:119], v137 offset:24576
	ds_read_b128 v[96:99], v137 offset:24832
	ds_read_b128 v[108:111], v137 offset:32768
	ds_read_b128 v[76:79], v137 offset:33024
	s_waitcnt lgkmcnt(14)
	v_pk_mul_f32 v[138:139], v[90:91], v[70:71]
	v_pk_mul_f32 v[70:71], v[94:95], v[70:71]
	v_pk_fma_f32 v[138:139], v[88:89], v[68:69], v[138:139]
	v_pk_fma_f32 v[68:69], v[92:93], v[68:69], v[70:71]
	v_add_f32_e32 v70, v138, v139
	v_cndmask_b32_e64 v138, v129, v128, s[6:7]
	v_cndmask_b32_e64 v139, v131, v130, s[6:7]
	v_cndmask_b32_e64 v128, v128, v129, s[6:7]
	v_cndmask_b32_e64 v129, v130, v131, s[6:7]
	v_add_f32_e32 v68, v68, v69
	v_add_f32_dpp v128, v138, v128 quad_perm:[1,0,3,2] row_mask:0xf bank_mask:0xf bound_ctrl:1
	v_add_f32_dpp v129, v139, v129 quad_perm:[1,0,3,2] row_mask:0xf bank_mask:0xf bound_ctrl:1
	v_add_f32_dpp v69, v70, v70 quad_perm:[1,0,3,2] row_mask:0xf bank_mask:0xf bound_ctrl:1
	v_add_f32_dpp v68, v68, v68 quad_perm:[1,0,3,2] row_mask:0xf bank_mask:0xf bound_ctrl:1
	v_cndmask_b32_e64 v130, v128, v129, s[8:9]
	v_cndmask_b32_e64 v128, v129, v128, s[8:9]
	v_add_f32_dpp v69, v69, v69 quad_perm:[2,3,0,1] row_mask:0xf bank_mask:0xf bound_ctrl:1
	v_add_f32_dpp v70, v68, v68 quad_perm:[2,3,0,1] row_mask:0xf bank_mask:0xf bound_ctrl:1
	v_add_f32_dpp v128, v130, v128 quad_perm:[2,3,0,1] row_mask:0xf bank_mask:0xf bound_ctrl:1
	v_add_f32_dpp v68, v69, v69 row_ror:4 row_mask:0xf bank_mask:0xf bound_ctrl:1
	v_add_f32_dpp v69, v70, v70 row_ror:4 row_mask:0xf bank_mask:0xf bound_ctrl:1
	v_add_f32_dpp v129, v128, v128 row_ror:4 row_mask:0xf bank_mask:0xf bound_ctrl:1
	s_nop 1
	v_add_f32_dpp v129, v129, v129 row_ror:8 row_mask:0xf bank_mask:0xf bound_ctrl:1
	s_and_saveexec_b64 s[78:79], s[10:11]
	ds_write_b32 v135, v129
	s_or_b64 exec, exec, s[78:79]
	v_pk_mul_f32 v[130:131], v[64:65], v[126:127] op_sel_hi:[1,0]
	v_pk_mul_f32 v[64:65], v[64:65], v[126:127] op_sel:[0,1]
	v_pk_fma_f32 v[88:89], v[88:89], v[60:61], v[130:131]
	v_pk_mul_f32 v[130:131], v[66:67], v[126:127] op_sel_hi:[1,0]
	v_pk_fma_f32 v[60:61], v[92:93], v[60:61], v[64:65]
	v_pk_mul_f32 v[64:65], v[66:67], v[126:127] op_sel:[0,1]
	v_pk_fma_f32 v[90:91], v[90:91], v[62:63], v[130:131]
	v_pk_fma_f32 v[62:63], v[94:95], v[62:63], v[64:65]
	v_add_f32_dpp v64, v68, v68 row_ror:8 row_mask:0xf bank_mask:0xf bound_ctrl:1
	v_add_f32_dpp v66, v69, v69 row_ror:8 row_mask:0xf bank_mask:0xf bound_ctrl:1
	v_pk_fma_f32 v[68:69], v[28:29], v[64:65], v[88:89] op_sel_hi:[1,0,1] neg_lo:[1,0,0] neg_hi:[1,0,0]
	v_pk_fma_f32 v[64:65], v[30:31], v[64:65], v[90:91] op_sel_hi:[1,0,1] neg_lo:[1,0,0] neg_hi:[1,0,0]
	v_pk_fma_f32 v[30:31], v[30:31], v[66:67], v[62:63] op_sel_hi:[1,0,1] neg_lo:[1,0,0] neg_hi:[1,0,0]
	v_pk_fma_f32 v[28:29], v[28:29], v[66:67], v[60:61] op_sel_hi:[1,0,1] neg_lo:[1,0,0] neg_hi:[1,0,0]
	v_pk_mul_f32 v[60:61], v[54:55], v[64:65]
	v_pk_mul_f32 v[54:55], v[54:55], v[30:31]
	v_pk_fma_f32 v[60:61], v[52:53], v[68:69], v[60:61]
	v_pk_fma_f32 v[52:53], v[52:53], v[28:29], v[54:55]
	v_add_f32_e32 v129, v60, v61
	v_add_f32_e32 v138, v52, v53
	v_pk_mul_f32 v[52:53], v[50:51], v[64:65]
	v_pk_mul_f32 v[50:51], v[50:51], v[30:31]
	v_pk_fma_f32 v[52:53], v[48:49], v[68:69], v[52:53]
	v_pk_fma_f32 v[48:49], v[48:49], v[28:29], v[50:51]
	v_add_f32_e32 v52, v52, v53
	v_add_f32_e32 v53, v48, v49
	v_pk_mul_f32 v[48:49], v[24:25], v[68:69]
	v_pk_mul_f32 v[24:25], v[24:25], v[28:29]
	v_add_f32_dpp v28, v52, v52 quad_perm:[1,0,3,2] row_mask:0xf bank_mask:0xf bound_ctrl:1
	v_add_f32_dpp v29, v53, v53 quad_perm:[1,0,3,2] row_mask:0xf bank_mask:0xf bound_ctrl:1
	v_pk_mul_f32 v[50:51], v[26:27], v[64:65]
	v_add_f32_dpp v28, v28, v28 quad_perm:[2,3,0,1] row_mask:0xf bank_mask:0xf bound_ctrl:1
	v_add_f32_dpp v29, v29, v29 quad_perm:[2,3,0,1] row_mask:0xf bank_mask:0xf bound_ctrl:1
	v_pk_mul_f32 v[26:27], v[26:27], v[30:31]
	v_add_f32_dpp v28, v28, v28 row_ror:4 row_mask:0xf bank_mask:0xf bound_ctrl:1
	v_add_f32_dpp v29, v29, v29 row_ror:4 row_mask:0xf bank_mask:0xf bound_ctrl:1
	s_waitcnt lgkmcnt(11)
	v_pk_fma_f32 v[50:51], v[58:59], v[124:125], v[50:51] op_sel_hi:[1,0,1]
	v_pk_fma_f32 v[26:27], v[58:59], v[124:125], v[26:27] op_sel:[0,1,0]
	v_add_f32_dpp v28, v28, v28 row_ror:8 row_mask:0xf bank_mask:0xf bound_ctrl:1
	v_add_f32_dpp v30, v29, v29 row_ror:8 row_mask:0xf bank_mask:0xf bound_ctrl:1
	v_pk_fma_f32 v[48:49], v[56:57], v[124:125], v[48:49] op_sel_hi:[1,0,1]
	v_pk_fma_f32 v[24:25], v[56:57], v[124:125], v[24:25] op_sel:[0,1,0]
	v_pk_fma_f32 v[90:91], v[18:19], v[28:29], v[50:51] op_sel_hi:[1,0,1] neg_lo:[1,0,0] neg_hi:[1,0,0]
	v_pk_fma_f32 v[88:89], v[18:19], v[30:31], v[26:27] op_sel_hi:[1,0,1] neg_lo:[1,0,0] neg_hi:[1,0,0]
	v_pk_fma_f32 v[94:95], v[16:17], v[28:29], v[48:49] op_sel_hi:[1,0,1] neg_lo:[1,0,0] neg_hi:[1,0,0]
	v_pk_fma_f32 v[92:93], v[16:17], v[30:31], v[24:25] op_sel_hi:[1,0,1] neg_lo:[1,0,0] neg_hi:[1,0,0]
	v_pk_mul_f32 v[16:17], v[22:23], v[90:91]
	v_pk_mul_f32 v[18:19], v[22:23], v[88:89]
	v_pk_fma_f32 v[16:17], v[20:21], v[94:95], v[16:17]
	v_pk_fma_f32 v[18:19], v[20:21], v[92:93], v[18:19]
	v_add_f32_e32 v139, v16, v17
	v_add_f32_e32 v140, v18, v19
	s_add_i32 s71, s47, 4
	s_cmp_ge_i32 s71, s24
	s_cselect_b64 s[78:79], -1, 0
	s_cmp_lt_i32 s71, s24
	s_cselect_b32 s28, s71, s47
	v_lshl_add_u32 v16, s28, 8, v133
	v_lshl_add_u32 v17, s28, 7, v134
	s_or_b32 s28, s28, 1
	v_lshl_add_u32 v56, s28, 8, v133
	ds_read_b128 v[68:71], v16 offset:8192
	ds_read_b128 v[28:31], v16 offset:16384
	ds_read_b128 v[60:63], v16
	ds_read_b128 v[52:55], v16 offset:32768
	ds_read_b128 v[64:67], v16 offset:24576
	ds_read_b64 v[126:127], v17 offset:40960
	ds_read_b128 v[48:51], v56 offset:8192
	ds_read_b128 v[16:19], v56 offset:16384
	ds_read_b128 v[24:27], v56
	ds_read_b128 v[20:23], v56 offset:32768
	v_lshl_add_u32 v124, s28, 7, v134
	ds_read_b128 v[56:59], v56 offset:24576
	ds_read_b64 v[124:125], v124 offset:40960
	s_waitcnt lgkmcnt(14)
	v_pk_mul_f32 v[130:131], v[122:123], v[90:91]
	v_pk_mul_f32 v[122:123], v[122:123], v[88:89]
	v_pk_fma_f32 v[130:131], v[120:121], v[94:95], v[130:131]
	v_pk_fma_f32 v[120:121], v[120:121], v[92:93], v[122:123]
	v_add_f32_e32 v122, v130, v131
	v_cndmask_b32_e64 v130, v129, v138, s[6:7]
	v_cndmask_b32_e64 v131, v139, v140, s[6:7]
	v_cndmask_b32_e64 v129, v138, v129, s[6:7]
	v_cndmask_b32_e64 v138, v140, v139, s[6:7]
	v_add_f32_e32 v120, v120, v121
	v_add_f32_dpp v129, v130, v129 quad_perm:[1,0,3,2] row_mask:0xf bank_mask:0xf bound_ctrl:1
	v_add_f32_dpp v130, v131, v138 quad_perm:[1,0,3,2] row_mask:0xf bank_mask:0xf bound_ctrl:1
	v_add_f32_dpp v121, v122, v122 quad_perm:[1,0,3,2] row_mask:0xf bank_mask:0xf bound_ctrl:1
	v_add_f32_dpp v120, v120, v120 quad_perm:[1,0,3,2] row_mask:0xf bank_mask:0xf bound_ctrl:1
	v_cndmask_b32_e64 v131, v129, v130, s[8:9]
	v_cndmask_b32_e64 v129, v130, v129, s[8:9]
	v_add_f32_dpp v121, v121, v121 quad_perm:[2,3,0,1] row_mask:0xf bank_mask:0xf bound_ctrl:1
	v_add_f32_dpp v122, v120, v120 quad_perm:[2,3,0,1] row_mask:0xf bank_mask:0xf bound_ctrl:1
	v_add_f32_dpp v129, v131, v129 quad_perm:[2,3,0,1] row_mask:0xf bank_mask:0xf bound_ctrl:1
	v_add_f32_dpp v120, v121, v121 row_ror:4 row_mask:0xf bank_mask:0xf bound_ctrl:1
	v_add_f32_dpp v121, v122, v122 row_ror:4 row_mask:0xf bank_mask:0xf bound_ctrl:1
	v_add_f32_dpp v129, v129, v129 row_ror:4 row_mask:0xf bank_mask:0xf bound_ctrl:1
	s_nop 1
	v_add_f32_dpp v129, v129, v129 row_ror:8 row_mask:0xf bank_mask:0xf bound_ctrl:1
	s_and_saveexec_b64 s[80:81], s[10:11]
	ds_write_b32 v135, v129 offset:256
	s_or_b64 exec, exec, s[80:81]
	v_pk_mul_f32 v[94:95], v[112:113], v[94:95]
	v_pk_mul_f32 v[90:91], v[114:115], v[90:91]
	v_pk_mul_f32 v[92:93], v[112:113], v[92:93]
	v_pk_mul_f32 v[88:89], v[114:115], v[88:89]
	v_pk_fma_f32 v[94:95], v[116:117], v[80:81], v[94:95] op_sel_hi:[1,0,1]
	v_pk_fma_f32 v[90:91], v[118:119], v[80:81], v[90:91] op_sel_hi:[1,0,1]
	v_pk_fma_f32 v[92:93], v[116:117], v[80:81], v[92:93] op_sel:[0,1,0]
	v_pk_fma_f32 v[80:81], v[118:119], v[80:81], v[88:89] op_sel:[0,1,0]
	v_add_f32_dpp v88, v120, v120 row_ror:8 row_mask:0xf bank_mask:0xf bound_ctrl:1
	v_add_f32_dpp v112, v121, v121 row_ror:8 row_mask:0xf bank_mask:0xf bound_ctrl:1
	v_pk_fma_f32 v[94:95], v[104:105], v[88:89], v[94:95] op_sel_hi:[1,0,1] neg_lo:[1,0,0] neg_hi:[1,0,0]
	v_pk_fma_f32 v[88:89], v[106:107], v[88:89], v[90:91] op_sel_hi:[1,0,1] neg_lo:[1,0,0] neg_hi:[1,0,0]
	v_pk_fma_f32 v[80:81], v[106:107], v[112:113], v[80:81] op_sel_hi:[1,0,1] neg_lo:[1,0,0] neg_hi:[1,0,0]
	v_pk_fma_f32 v[90:91], v[104:105], v[112:113], v[92:93] op_sel_hi:[1,0,1] neg_lo:[1,0,0] neg_hi:[1,0,0]
	s_waitcnt lgkmcnt(13)
	v_pk_mul_f32 v[92:93], v[110:111], v[88:89]
	v_pk_mul_f32 v[104:105], v[110:111], v[80:81]
	v_pk_fma_f32 v[92:93], v[108:109], v[94:95], v[92:93]
	v_pk_fma_f32 v[104:105], v[108:109], v[90:91], v[104:105]
	v_add_f32_e32 v128, v104, v105
	v_add_f32_e32 v129, v92, v93
	v_pk_mul_f32 v[92:93], v[102:103], v[88:89]
	v_pk_mul_f32 v[102:103], v[102:103], v[80:81]
	v_pk_fma_f32 v[92:93], v[100:101], v[94:95], v[92:93]
	v_pk_fma_f32 v[100:101], v[100:101], v[90:91], v[102:103]
	v_add_f32_e32 v102, v92, v93
	v_add_f32_e32 v100, v100, v101
	v_pk_mul_f32 v[92:93], v[84:85], v[94:95]
	v_pk_mul_f32 v[88:89], v[86:87], v[88:89]
	v_pk_mul_f32 v[84:85], v[84:85], v[90:91]
	v_pk_mul_f32 v[80:81], v[86:87], v[80:81]
	v_pk_fma_f32 v[92:93], v[96:97], v[82:83], v[92:93] op_sel_hi:[1,0,1]
	v_pk_fma_f32 v[94:95], v[98:99], v[82:83], v[88:89] op_sel_hi:[1,0,1]
	v_pk_fma_f32 v[84:85], v[96:97], v[82:83], v[84:85] op_sel:[0,1,0]
	v_pk_fma_f32 v[80:81], v[98:99], v[82:83], v[80:81] op_sel:[0,1,0]
	v_add_f32_dpp v82, v102, v102 quad_perm:[1,0,3,2] row_mask:0xf bank_mask:0xf bound_ctrl:1
	v_add_f32_dpp v83, v100, v100 quad_perm:[1,0,3,2] row_mask:0xf bank_mask:0xf bound_ctrl:1
	s_nop 0
	v_add_f32_dpp v82, v82, v82 quad_perm:[2,3,0,1] row_mask:0xf bank_mask:0xf bound_ctrl:1
	v_add_f32_dpp v83, v83, v83 quad_perm:[2,3,0,1] row_mask:0xf bank_mask:0xf bound_ctrl:1
	s_nop 0
	v_add_f32_dpp v82, v82, v82 row_ror:4 row_mask:0xf bank_mask:0xf bound_ctrl:1
	v_add_f32_dpp v83, v83, v83 row_ror:4 row_mask:0xf bank_mask:0xf bound_ctrl:1
	s_nop 0
	v_add_f32_dpp v82, v82, v82 row_ror:8 row_mask:0xf bank_mask:0xf bound_ctrl:1
	v_add_f32_dpp v86, v83, v83 row_ror:8 row_mask:0xf bank_mask:0xf bound_ctrl:1
	v_pk_fma_f32 v[90:91], v[74:75], v[82:83], v[94:95] op_sel_hi:[1,0,1] neg_lo:[1,0,0] neg_hi:[1,0,0]
	v_pk_fma_f32 v[94:95], v[74:75], v[86:87], v[80:81] op_sel_hi:[1,0,1] neg_lo:[1,0,0] neg_hi:[1,0,0]
	v_pk_fma_f32 v[88:89], v[72:73], v[82:83], v[92:93] op_sel_hi:[1,0,1] neg_lo:[1,0,0] neg_hi:[1,0,0]
	v_pk_fma_f32 v[92:93], v[72:73], v[86:87], v[84:85] op_sel_hi:[1,0,1] neg_lo:[1,0,0] neg_hi:[1,0,0]
	s_waitcnt lgkmcnt(12)
	v_pk_mul_f32 v[72:73], v[78:79], v[90:91]
	v_pk_mul_f32 v[74:75], v[78:79], v[94:95]
	v_pk_fma_f32 v[72:73], v[76:77], v[88:89], v[72:73]
	v_pk_fma_f32 v[74:75], v[76:77], v[92:93], v[74:75]
	v_add_f32_e32 v130, v74, v75
	v_add_f32_e32 v131, v72, v73
	v_add_u32_e32 v135, 0x200, v135
	v_add_u32_e32 v136, 0x200, v136
	v_add_u32_e32 v137, 0x400, v137
	s_and_b64 vcc, exec, s[78:79]
	s_cbranch_vccnz .LBB0_372
	s_mov_b32 s47, s71
	s_branch .LBB0_365
